# SCAN chunk loop: B1-B2 region (CB tiles, Yoff, state) rewritten with batched/pipelined LDS reads, same MFMA order; on top of softplus change
# speedup vs baseline: 1.0303x; 1.0025x over previous
; #define LAS __attribute__((address_space(3)))
; #define MFMA16(a, b, c) __builtin_amdgcn_mfma_f32_16x16x32_bf16((a), (b), (c), 0, 0, 0)
; #define MFMA16(a, b, c) __builtin_amdgcn_mfma_f32_16x16x32_bf16((a), (b), (c), 0, 0, 0)
; __device__ __forceinline__ void scan_prompt_unit(const Ctx& c, int b, int h) {
;     ...
;         bf16x8 cf[4];
; #pragma unroll
;         for (int k = 0; k < 4; ++k) cf[k] = *(const LAS bf16x8*)(lds + SC_C + (16 * w + c16) * SROW + (32 * k + 8 * q) * 2);
;         f32x4 cb[8];
; #pragma unroll
;         for (int st = 0; st < 8; ++st) {
;             cb[st] = (f32x4){0.f, 0.f, 0.f, 0.f};
;             if (st <= w) {
; #pragma unroll
;                 for (int k = 0; k < 4; ++k) { const bf16x8 bf = *(const LAS bf16x8*)(lds + SC_B + (16 * st + c16) * SROW + (32 * k + 8 * q) * 2); cb[st] = MFMA16(bf, cf[k], cb[st]); }
;             }
;         }
.LBB0_155:
	v_add_u32_e32 v218, v191, v192
	ds_read_b128 v[116:119], v218
	ds_read_b128 v[112:115], v218 offset:64
	ds_read_b128 v[108:111], v218 offset:128
	ds_read_b128 v[72:75], v218 offset:192
	ds_read_b128 v[60:63], v206 offset:34816
	ds_read_b128 v[64:67], v206 offset:34880
	ds_read_b128 v[68:71], v206 offset:34944
	ds_read_b128 v[120:123], v206 offset:35008
	s_andn2_b64 s[22:23], exec, s[24:25]
	s_andn2_b64 s[20:21], exec, s[26:27]
	s_andn2_b64 s[18:19], exec, s[36:37]
	s_andn2_b64 s[16:17], exec, s[50:51]
	s_andn2_b64 s[14:15], exec, s[52:53]
	s_andn2_b64 s[12:13], exec, s[54:55]
	s_andn2_b64 s[10:11], exec, s[56:57]
	s_and_b64 vcc, exec, s[26:27]
	s_cbranch_vccz .Lscb_t0_last
	ds_read_b128 v[124:127], v206 offset:39168
	ds_read_b128 v[128:131], v206 offset:39232
	ds_read_b128 v[132:135], v206 offset:39296
	ds_read_b128 v[136:139], v206 offset:39360
	s_and_b64 vcc, exec, s[36:37]
	s_cbranch_vccz .Lscb_tail0
	ds_read_b128 v[238:241], v206 offset:43520
	ds_read_b128 v[242:245], v206 offset:43584
	ds_read_b128 v[246:249], v206 offset:43648
	ds_read_b128 v[148:151], v206 offset:43712
	v_mov_b32_e32 v96, 0
	v_mov_b32_e32 v97, 0
	v_mov_b32_e32 v98, 0
	v_mov_b32_e32 v99, 0
	v_mov_b32_e32 v100, 0
	v_mov_b32_e32 v101, 0
	v_mov_b32_e32 v102, 0
	v_mov_b32_e32 v103, 0
	v_mov_b32_e32 v88, 0
	v_mov_b32_e32 v89, 0
	v_mov_b32_e32 v90, 0
	v_mov_b32_e32 v91, 0
	v_mov_b32_e32 v92, 0
	v_mov_b32_e32 v93, 0
	v_mov_b32_e32 v94, 0
	v_mov_b32_e32 v95, 0
	v_mov_b32_e32 v76, 0
	v_mov_b32_e32 v77, 0
	v_mov_b32_e32 v78, 0
	v_mov_b32_e32 v79, 0
	v_mov_b32_e32 v84, 0
	v_mov_b32_e32 v85, 0
	v_mov_b32_e32 v86, 0
	v_mov_b32_e32 v87, 0
	v_mov_b32_e32 v80, 0
	v_mov_b32_e32 v81, 0
	v_mov_b32_e32 v82, 0
	v_mov_b32_e32 v83, 0
	s_waitcnt lgkmcnt(8)
	v_mfma_f32_16x16x32_bf16 v[104:107], v[60:63], v[116:119], 0
	v_mfma_f32_16x16x32_bf16 v[104:107], v[64:67], v[112:115], v[104:107]
	v_mfma_f32_16x16x32_bf16 v[104:107], v[68:71], v[108:111], v[104:107]
	v_mfma_f32_16x16x32_bf16 v[104:107], v[120:123], v[72:75], v[104:107]
	s_and_b64 vcc, exec, s[50:51]
	s_cbranch_vccz .Lscb_tail1
	ds_read_b128 v[60:63], v206 offset:47872
	ds_read_b128 v[64:67], v206 offset:47936
	ds_read_b128 v[68:71], v206 offset:48000
	ds_read_b128 v[120:123], v206 offset:48064
	s_waitcnt lgkmcnt(8)
	v_mfma_f32_16x16x32_bf16 v[96:99], v[124:127], v[116:119], 0
	v_mfma_f32_16x16x32_bf16 v[96:99], v[128:131], v[112:115], v[96:99]
	v_mfma_f32_16x16x32_bf16 v[96:99], v[132:135], v[108:111], v[96:99]
	v_mfma_f32_16x16x32_bf16 v[96:99], v[136:139], v[72:75], v[96:99]
	s_and_b64 vcc, exec, s[52:53]
	s_cbranch_vccz .Lscb_tail2
	ds_read_b128 v[124:127], v206 offset:52224
	ds_read_b128 v[128:131], v206 offset:52288
	ds_read_b128 v[132:135], v206 offset:52352
	ds_read_b128 v[136:139], v206 offset:52416
	s_waitcnt lgkmcnt(8)
	v_mfma_f32_16x16x32_bf16 v[100:103], v[238:241], v[116:119], 0
	v_mfma_f32_16x16x32_bf16 v[100:103], v[242:245], v[112:115], v[100:103]
	v_mfma_f32_16x16x32_bf16 v[100:103], v[246:249], v[108:111], v[100:103]
	v_mfma_f32_16x16x32_bf16 v[100:103], v[148:151], v[72:75], v[100:103]
	s_and_b64 vcc, exec, s[54:55]
	s_cbranch_vccz .Lscb_tail3
	ds_read_b128 v[238:241], v206 offset:56576
	ds_read_b128 v[242:245], v206 offset:56640
	ds_read_b128 v[246:249], v206 offset:56704
	ds_read_b128 v[148:151], v206 offset:56768
	s_waitcnt lgkmcnt(8)
	v_mfma_f32_16x16x32_bf16 v[88:91], v[60:63], v[116:119], 0
	v_mfma_f32_16x16x32_bf16 v[88:91], v[64:67], v[112:115], v[88:91]
	v_mfma_f32_16x16x32_bf16 v[88:91], v[68:71], v[108:111], v[88:91]
	v_mfma_f32_16x16x32_bf16 v[88:91], v[120:123], v[72:75], v[88:91]
	s_and_b64 vcc, exec, s[56:57]
	s_cbranch_vccz .Lscb_tail4
	ds_read_b128 v[60:63], v206 offset:60928
	ds_read_b128 v[64:67], v206 offset:60992
	ds_read_b128 v[68:71], v206 offset:61056
	ds_read_b128 v[120:123], v206 offset:61120
	s_waitcnt lgkmcnt(8)
	v_mfma_f32_16x16x32_bf16 v[92:95], v[124:127], v[116:119], 0
	v_mfma_f32_16x16x32_bf16 v[92:95], v[128:131], v[112:115], v[92:95]
	v_mfma_f32_16x16x32_bf16 v[92:95], v[132:135], v[108:111], v[92:95]
	v_mfma_f32_16x16x32_bf16 v[92:95], v[136:139], v[72:75], v[92:95]
	s_and_b64 vcc, exec, s[58:59]
	s_cbranch_vccz .Lscb_tail5
	ds_read_b128 v[124:127], v206 offset:65280
	ds_read_b128 v[128:131], v206 offset:65344
	ds_read_b128 v[132:135], v206 offset:65408
	ds_read_b128 v[136:139], v206 offset:65472
	s_waitcnt lgkmcnt(8)
	v_mfma_f32_16x16x32_bf16 v[76:79], v[238:241], v[116:119], 0
	v_mfma_f32_16x16x32_bf16 v[76:79], v[242:245], v[112:115], v[76:79]
	v_mfma_f32_16x16x32_bf16 v[76:79], v[246:249], v[108:111], v[76:79]
	v_mfma_f32_16x16x32_bf16 v[76:79], v[148:151], v[72:75], v[76:79]
	s_waitcnt lgkmcnt(4)
	v_mfma_f32_16x16x32_bf16 v[84:87], v[60:63], v[116:119], 0
	v_mfma_f32_16x16x32_bf16 v[84:87], v[64:67], v[112:115], v[84:87]
	v_mfma_f32_16x16x32_bf16 v[84:87], v[68:71], v[108:111], v[84:87]
	v_mfma_f32_16x16x32_bf16 v[84:87], v[120:123], v[72:75], v[84:87]
	s_waitcnt lgkmcnt(0)
	v_mfma_f32_16x16x32_bf16 v[80:83], v[124:127], v[116:119], 0
	v_mfma_f32_16x16x32_bf16 v[80:83], v[128:131], v[112:115], v[80:83]
	v_mfma_f32_16x16x32_bf16 v[80:83], v[132:135], v[108:111], v[80:83]
	v_mfma_f32_16x16x32_bf16 v[80:83], v[136:139], v[72:75], v[80:83]
	s_branch .Lscb_done
; #define LAS __attribute__((address_space(3)))
; #define MFMA16(a, b, c) __builtin_amdgcn_mfma_f32_16x16x32_bf16((a), (b), (c), 0, 0, 0)
; #define MFMA16(a, b, c) __builtin_amdgcn_mfma_f32_16x16x32_bf16((a), (b), (c), 0, 0, 0)
; __device__ __forceinline__ void scan_prompt_unit(const Ctx& c, int b, int h) {
;     ...
;             cb[st] = (f32x4){0.f, 0.f, 0.f, 0.f};
;             if (st <= w) {
; #pragma unroll
;                 for (int k = 0; k < 4; ++k) { const bf16x8 bf = *(const LAS bf16x8*)(lds + SC_B + (16 * st + c16) * SROW + (32 * k + 8 * q) * 2); cb[st] = MFMA16(bf, cf[k], cb[st]); }
;             }
;         }
.Lscb_tail0:
	v_mov_b32_e32 v96, 0
	v_mov_b32_e32 v97, 0
	v_mov_b32_e32 v98, 0
	v_mov_b32_e32 v99, 0
	v_mov_b32_e32 v100, 0
	v_mov_b32_e32 v101, 0
	v_mov_b32_e32 v102, 0
	v_mov_b32_e32 v103, 0
	v_mov_b32_e32 v88, 0
	v_mov_b32_e32 v89, 0
	v_mov_b32_e32 v90, 0
	v_mov_b32_e32 v91, 0
	v_mov_b32_e32 v92, 0
	v_mov_b32_e32 v93, 0
	v_mov_b32_e32 v94, 0
	v_mov_b32_e32 v95, 0
	v_mov_b32_e32 v76, 0
	v_mov_b32_e32 v77, 0
	v_mov_b32_e32 v78, 0
	v_mov_b32_e32 v79, 0
	v_mov_b32_e32 v84, 0
	v_mov_b32_e32 v85, 0
	v_mov_b32_e32 v86, 0
	v_mov_b32_e32 v87, 0
	v_mov_b32_e32 v80, 0
	v_mov_b32_e32 v81, 0
	v_mov_b32_e32 v82, 0
	v_mov_b32_e32 v83, 0
	s_waitcnt lgkmcnt(4)
	v_mfma_f32_16x16x32_bf16 v[104:107], v[60:63], v[116:119], 0
	v_mfma_f32_16x16x32_bf16 v[104:107], v[64:67], v[112:115], v[104:107]
	v_mfma_f32_16x16x32_bf16 v[104:107], v[68:71], v[108:111], v[104:107]
	v_mfma_f32_16x16x32_bf16 v[104:107], v[120:123], v[72:75], v[104:107]
	s_waitcnt lgkmcnt(0)
	v_mfma_f32_16x16x32_bf16 v[96:99], v[124:127], v[116:119], 0
	v_mfma_f32_16x16x32_bf16 v[96:99], v[128:131], v[112:115], v[96:99]
	v_mfma_f32_16x16x32_bf16 v[96:99], v[132:135], v[108:111], v[96:99]
	v_mfma_f32_16x16x32_bf16 v[96:99], v[136:139], v[72:75], v[96:99]
	s_branch .Lscb_done
.Lscb_tail1:
	s_waitcnt lgkmcnt(4)
	v_mfma_f32_16x16x32_bf16 v[96:99], v[124:127], v[116:119], 0
	v_mfma_f32_16x16x32_bf16 v[96:99], v[128:131], v[112:115], v[96:99]
	v_mfma_f32_16x16x32_bf16 v[96:99], v[132:135], v[108:111], v[96:99]
	v_mfma_f32_16x16x32_bf16 v[96:99], v[136:139], v[72:75], v[96:99]
	s_waitcnt lgkmcnt(0)
	v_mfma_f32_16x16x32_bf16 v[100:103], v[238:241], v[116:119], 0
	v_mfma_f32_16x16x32_bf16 v[100:103], v[242:245], v[112:115], v[100:103]
	v_mfma_f32_16x16x32_bf16 v[100:103], v[246:249], v[108:111], v[100:103]
	v_mfma_f32_16x16x32_bf16 v[100:103], v[148:151], v[72:75], v[100:103]
	s_branch .Lscb_done
.Lscb_tail2:
	s_waitcnt lgkmcnt(4)
	v_mfma_f32_16x16x32_bf16 v[100:103], v[238:241], v[116:119], 0
	v_mfma_f32_16x16x32_bf16 v[100:103], v[242:245], v[112:115], v[100:103]
	v_mfma_f32_16x16x32_bf16 v[100:103], v[246:249], v[108:111], v[100:103]
	v_mfma_f32_16x16x32_bf16 v[100:103], v[148:151], v[72:75], v[100:103]
	s_waitcnt lgkmcnt(0)
	v_mfma_f32_16x16x32_bf16 v[88:91], v[60:63], v[116:119], 0
	v_mfma_f32_16x16x32_bf16 v[88:91], v[64:67], v[112:115], v[88:91]
	v_mfma_f32_16x16x32_bf16 v[88:91], v[68:71], v[108:111], v[88:91]
	v_mfma_f32_16x16x32_bf16 v[88:91], v[120:123], v[72:75], v[88:91]
	s_branch .Lscb_done
.Lscb_tail3:
	s_waitcnt lgkmcnt(4)
	v_mfma_f32_16x16x32_bf16 v[88:91], v[60:63], v[116:119], 0
	v_mfma_f32_16x16x32_bf16 v[88:91], v[64:67], v[112:115], v[88:91]
	v_mfma_f32_16x16x32_bf16 v[88:91], v[68:71], v[108:111], v[88:91]
	v_mfma_f32_16x16x32_bf16 v[88:91], v[120:123], v[72:75], v[88:91]
	s_waitcnt lgkmcnt(0)
	v_mfma_f32_16x16x32_bf16 v[92:95], v[124:127], v[116:119], 0
	v_mfma_f32_16x16x32_bf16 v[92:95], v[128:131], v[112:115], v[92:95]
	v_mfma_f32_16x16x32_bf16 v[92:95], v[132:135], v[108:111], v[92:95]
	v_mfma_f32_16x16x32_bf16 v[92:95], v[136:139], v[72:75], v[92:95]
	s_branch .Lscb_done
.Lscb_tail4:
	s_waitcnt lgkmcnt(4)
	v_mfma_f32_16x16x32_bf16 v[92:95], v[124:127], v[116:119], 0
	v_mfma_f32_16x16x32_bf16 v[92:95], v[128:131], v[112:115], v[92:95]
	v_mfma_f32_16x16x32_bf16 v[92:95], v[132:135], v[108:111], v[92:95]
	v_mfma_f32_16x16x32_bf16 v[92:95], v[136:139], v[72:75], v[92:95]
	s_waitcnt lgkmcnt(0)
	v_mfma_f32_16x16x32_bf16 v[76:79], v[238:241], v[116:119], 0
	v_mfma_f32_16x16x32_bf16 v[76:79], v[242:245], v[112:115], v[76:79]
	v_mfma_f32_16x16x32_bf16 v[76:79], v[246:249], v[108:111], v[76:79]
	v_mfma_f32_16x16x32_bf16 v[76:79], v[148:151], v[72:75], v[76:79]
	s_branch .Lscb_done
.Lscb_tail5:
	s_waitcnt lgkmcnt(4)
	v_mfma_f32_16x16x32_bf16 v[76:79], v[238:241], v[116:119], 0
	v_mfma_f32_16x16x32_bf16 v[76:79], v[242:245], v[112:115], v[76:79]
	v_mfma_f32_16x16x32_bf16 v[76:79], v[246:249], v[108:111], v[76:79]
	v_mfma_f32_16x16x32_bf16 v[76:79], v[148:151], v[72:75], v[76:79]
	s_waitcnt lgkmcnt(0)
	v_mfma_f32_16x16x32_bf16 v[84:87], v[60:63], v[116:119], 0
	v_mfma_f32_16x16x32_bf16 v[84:87], v[64:67], v[112:115], v[84:87]
	v_mfma_f32_16x16x32_bf16 v[84:87], v[68:71], v[108:111], v[84:87]
	v_mfma_f32_16x16x32_bf16 v[84:87], v[120:123], v[72:75], v[84:87]
	s_branch .Lscb_done
.Lscb_t0_last:
	v_mov_b32_e32 v96, 0
	v_mov_b32_e32 v97, 0
	v_mov_b32_e32 v98, 0
	v_mov_b32_e32 v99, 0
	v_mov_b32_e32 v100, 0
	v_mov_b32_e32 v101, 0
	v_mov_b32_e32 v102, 0
	v_mov_b32_e32 v103, 0
	v_mov_b32_e32 v88, 0
	v_mov_b32_e32 v89, 0
	v_mov_b32_e32 v90, 0
	v_mov_b32_e32 v91, 0
	v_mov_b32_e32 v92, 0
	v_mov_b32_e32 v93, 0
	v_mov_b32_e32 v94, 0
	v_mov_b32_e32 v95, 0
	v_mov_b32_e32 v76, 0
	v_mov_b32_e32 v77, 0
	v_mov_b32_e32 v78, 0
	v_mov_b32_e32 v79, 0
	v_mov_b32_e32 v84, 0
	v_mov_b32_e32 v85, 0
	v_mov_b32_e32 v86, 0
	v_mov_b32_e32 v87, 0
	v_mov_b32_e32 v80, 0
	v_mov_b32_e32 v81, 0
	v_mov_b32_e32 v82, 0
	v_mov_b32_e32 v83, 0
	s_waitcnt lgkmcnt(0)
	v_mfma_f32_16x16x32_bf16 v[104:107], v[60:63], v[116:119], 0
	v_mfma_f32_16x16x32_bf16 v[104:107], v[64:67], v[112:115], v[104:107]
	v_mfma_f32_16x16x32_bf16 v[104:107], v[68:71], v[108:111], v[104:107]
	v_mfma_f32_16x16x32_bf16 v[104:107], v[120:123], v[72:75], v[104:107]
; #define LAS __attribute__((address_space(3)))
; #define MFMA16(a, b, c) __builtin_amdgcn_mfma_f32_16x16x32_bf16((a), (b), (c), 0, 0, 0)
; #define MFMA16(a, b, c) __builtin_amdgcn_mfma_f32_16x16x32_bf16((a), (b), (c), 0, 0, 0)
; __device__ __forceinline__ void scan_prompt_unit(const Ctx& c, int b, int h) {
;     ...
;         f32x4 yo[4];
; #pragma unroll
;         for (int pt = 0; pt < 4; ++pt) {
;             yo[pt] = (f32x4){0.f, 0.f, 0.f, 0.f};
; #pragma unroll
;             for (int k = 0; k < 4; ++k) { const bf16x8 hf = *(const LAS bf16x8*)(lds + SC_H + (16 * pt + c16) * SROW + (32 * k + 8 * q) * 2); yo[pt] = MFMA16(hf, cf[k], yo[pt]); }
;         }
;         bf16x8 xf[2][4];
;         {
;             const float cdec = __expf(acs_last);
; #pragma unroll
;             for (int pt = 0; pt < 4; ++pt) hacc[pt] = hacc[pt] * cdec;
; #pragma unroll
;             for (int kl = 0; kl < 4; ++kl) {
;                 const bf16x8 btf = tr_frag(lds + SC_BS, SROW, 32 * kl, 16 * w, lane);
; #pragma unroll
;                 for (int pt = 0; pt < 4; ++pt) {
;                     const bf16x8 x_ = tr_frag(lds + SC_X, XROW, 32 * kl, 16 * pt, lane);
;                     if (kl < 2) xf[kl][pt] = x_;
;                     hacc[pt] = MFMA16(btf, x_, hacc[pt]);
;                 }
;             }
;         }
.Lscb_done:
	ds_read_b128 v[124:127], v202
	ds_read_b128 v[128:131], v202 offset:64
	ds_read_b128 v[132:135], v202 offset:128
	ds_read_b128 v[136:139], v202 offset:192
	ds_read_b128 v[238:241], v202 offset:4352
	ds_read_b128 v[242:245], v202 offset:4416
	ds_read_b128 v[246:249], v202 offset:4480
	ds_read_b128 v[148:151], v202 offset:4544
	v_mul_f32_e32 v0, 0x3fb8aa3b, v0
	v_exp_f32_e32 v0, v0
	v_add_u32_e32 v3, v191, v196
	s_nop 0
	v_mul_f32_e64 v46, v46, v0
	v_mul_f32_e64 v47, v47, v0
	v_pk_mul_f32 v[44:45], v[44:45], v[0:1] op_sel_hi:[1,0]
	v_pk_mul_f32 v[50:51], v[50:51], v[0:1] op_sel_hi:[1,0]
	v_pk_mul_f32 v[48:49], v[48:49], v[0:1] op_sel_hi:[1,0]
	v_pk_mul_f32 v[54:55], v[54:55], v[0:1] op_sel_hi:[1,0]
	v_pk_mul_f32 v[52:53], v[52:53], v[0:1] op_sel_hi:[1,0]
	v_pk_mul_f32 v[58:59], v[58:59], v[0:1] op_sel_hi:[1,0]
	v_pk_mul_f32 v[56:57], v[56:57], v[0:1] op_sel_hi:[1,0]
	s_waitcnt lgkmcnt(4)
	v_mfma_f32_16x16x32_bf16 v[60:63], v[124:127], v[116:119], 0
	v_mfma_f32_16x16x32_bf16 v[60:63], v[128:131], v[112:115], v[60:63]
	v_mfma_f32_16x16x32_bf16 v[60:63], v[132:135], v[108:111], v[60:63]
	v_mfma_f32_16x16x32_bf16 v[60:63], v[136:139], v[72:75], v[60:63]
	ds_read_b128 v[124:127], v202 offset:8704
	ds_read_b128 v[128:131], v202 offset:8768
	ds_read_b128 v[132:135], v202 offset:8832
	ds_read_b128 v[136:139], v202 offset:8896
	s_waitcnt lgkmcnt(4)
	v_mfma_f32_16x16x32_bf16 v[68:71], v[238:241], v[116:119], 0
	v_mfma_f32_16x16x32_bf16 v[68:71], v[242:245], v[112:115], v[68:71]
	v_mfma_f32_16x16x32_bf16 v[68:71], v[246:249], v[108:111], v[68:71]
	v_mfma_f32_16x16x32_bf16 v[68:71], v[148:151], v[72:75], v[68:71]
	ds_read_b128 v[238:241], v202 offset:13056
	ds_read_b128 v[242:245], v202 offset:13120
	ds_read_b128 v[246:249], v202 offset:13184
	ds_read_b128 v[148:151], v202 offset:13248
	s_waitcnt lgkmcnt(4)
	v_mfma_f32_16x16x32_bf16 v[64:67], v[124:127], v[116:119], 0
	v_mfma_f32_16x16x32_bf16 v[64:67], v[128:131], v[112:115], v[64:67]
	v_mfma_f32_16x16x32_bf16 v[64:67], v[132:135], v[108:111], v[64:67]
	v_mfma_f32_16x16x32_bf16 v[64:67], v[136:139], v[72:75], v[64:67]
	s_waitcnt lgkmcnt(0)
	v_mfma_f32_16x16x32_bf16 v[116:119], v[238:241], v[116:119], 0
	v_mfma_f32_16x16x32_bf16 v[112:115], v[242:245], v[112:115], v[116:119]
	v_mfma_f32_16x16x32_bf16 v[108:111], v[246:249], v[108:111], v[112:115]
	v_mfma_f32_16x16x32_bf16 v[72:75], v[148:151], v[72:75], v[108:111]
	ds_read_b64_tr_b16 v[224:225], v203
	ds_read_b64_tr_b16 v[226:227], v203 offset:1088
	ds_read_b64_tr_b16 v[220:221], v203 offset:8704
	ds_read_b64_tr_b16 v[222:223], v203 offset:9792
	ds_read_b64_tr_b16 v[124:125], v207 offset:96
	ds_read_b64_tr_b16 v[126:127], v207 offset:672
	ds_read_b64_tr_b16 v[120:121], v207 offset:4608
	ds_read_b64_tr_b16 v[122:123], v207 offset:5184
	ds_read_b64_tr_b16 v[128:129], v207 offset:4640
	ds_read_b64_tr_b16 v[130:131], v207 offset:5216
	ds_read_b64_tr_b16 v[132:133], v207 offset:4672
	ds_read_b64_tr_b16 v[134:135], v207 offset:5248
	ds_read_b64_tr_b16 v[136:137], v207 offset:4704
	ds_read_b64_tr_b16 v[138:139], v207 offset:5280
	s_nop 7
	ds_read_b64_tr_b16 v[112:113], v207
	ds_read_b64_tr_b16 v[114:115], v207 offset:576
	ds_read_b64_tr_b16 v[108:109], v207 offset:32
	ds_read_b64_tr_b16 v[110:111], v207 offset:608
	ds_read_b64_tr_b16 v[116:117], v207 offset:64
	ds_read_b64_tr_b16 v[118:119], v207 offset:640
	s_waitcnt lgkmcnt(0)
	v_mfma_f32_16x16x32_bf16 v[44:47], v[224:227], v[112:115], v[44:47]
	v_mfma_f32_16x16x32_bf16 v[48:51], v[224:227], v[108:111], v[48:51]
	v_mfma_f32_16x16x32_bf16 v[52:55], v[224:227], v[116:119], v[52:55]
	v_mfma_f32_16x16x32_bf16 v[56:59], v[224:227], v[124:127], v[56:59]
	ds_read_b64_tr_b16 v[224:225], v203 offset:17408
	ds_read_b64_tr_b16 v[226:227], v203 offset:18496
	ds_read_b64_tr_b16 v[238:239], v207 offset:9216
	ds_read_b64_tr_b16 v[240:241], v207 offset:9792
	ds_read_b64_tr_b16 v[242:243], v207 offset:9248
	ds_read_b64_tr_b16 v[244:245], v207 offset:9824
	ds_read_b64_tr_b16 v[246:247], v207 offset:9280
	ds_read_b64_tr_b16 v[248:249], v207 offset:9856
	ds_read_b64_tr_b16 v[148:149], v207 offset:9312
	ds_read_b64_tr_b16 v[150:151], v207 offset:9888
	v_mfma_f32_16x16x32_bf16 v[44:47], v[220:223], v[120:123], v[44:47]
	v_mfma_f32_16x16x32_bf16 v[48:51], v[220:223], v[128:131], v[48:51]
	v_mfma_f32_16x16x32_bf16 v[52:55], v[220:223], v[132:135], v[52:55]
	v_mfma_f32_16x16x32_bf16 v[56:59], v[220:223], v[136:139], v[56:59]
	s_waitcnt lgkmcnt(0)
	v_mfma_f32_16x16x32_bf16 v[44:47], v[224:227], v[238:241], v[44:47]
	v_mfma_f32_16x16x32_bf16 v[48:51], v[224:227], v[242:245], v[48:51]
	v_mfma_f32_16x16x32_bf16 v[52:55], v[224:227], v[246:249], v[52:55]
	v_mfma_f32_16x16x32_bf16 v[56:59], v[224:227], v[148:151], v[56:59]
	ds_read_b64_tr_b16 v[220:221], v203 offset:26112
	ds_read_b64_tr_b16 v[222:223], v203 offset:27200
	ds_read_b64_tr_b16 v[238:239], v207 offset:13824
	ds_read_b64_tr_b16 v[240:241], v207 offset:14400
	ds_read_b64_tr_b16 v[242:243], v207 offset:13856
	ds_read_b64_tr_b16 v[244:245], v207 offset:14432
	ds_read_b64_tr_b16 v[246:247], v207 offset:13888
	ds_read_b64_tr_b16 v[248:249], v207 offset:14464
	ds_read_b64_tr_b16 v[148:149], v207 offset:13920
	ds_read_b64_tr_b16 v[150:151], v207 offset:14496
	s_and_b64 vcc, exec, s[22:23]
	s_waitcnt lgkmcnt(0)
	v_mfma_f32_16x16x32_bf16 v[44:47], v[220:223], v[238:241], v[44:47]
	v_mfma_f32_16x16x32_bf16 v[48:51], v[220:223], v[242:245], v[48:51]
	v_mfma_f32_16x16x32_bf16 v[52:55], v[220:223], v[246:249], v[52:55]
	v_mfma_f32_16x16x32_bf16 v[56:59], v[220:223], v[148:151], v[56:59]
	s_barrier
; #define LAS __attribute__((address_space(3)))
; __device__ __forceinline__ unsigned cvt_pk_bf16(float lo, float hi) { f32x2 v = {lo, hi}; bf16x2_t b = __builtin_convertvector(v, bf16x2_t); return __builtin_bit_cast(unsigned, b); }
; __device__ __forceinline__ void scan_prompt_unit(const Ctx& c, int b, int h) {
;     ...
;         {
;             const int l = 16 * w + c16; const float acs_l = acsL[l];
; #pragma unroll
;             for (int st = 0; st < 8; ++st) {
;                 if (st <= (w | 1)) {
;                     u32x2 pk; pk.x = 0u; pk.y = 0u;
;                     if (st <= w) {
;                         const f32x4 as = *(const LAS f32x4*)(acsL + 16 * st + 4 * q), ds = *(const LAS f32x4*)(dtL + 16 * st + 4 * q);
;                         float v[4];
; #pragma unroll
;                         for (int r = 0; r < 4; ++r) { const int s_ = 16 * st + 4 * q + r; const float e = __expf(acs_l - as[r]) * ds[r] * cb[st][r]; v[r] = (s_ <= l) ? e : 0.f; }
;                         pk.x = cvt_pk_bf16(v[0], v[1]); pk.y = cvt_pk_bf16(v[2], v[3]);
;                     }
;                     *(LAS u32x2*)(lds + SC_B + l * SROW + (16 * st + 4 * q) * 2) = pk;
;                 }
;             }
;         }
	ds_read_b32 v219, v193
	s_cbranch_vccnz .LBB0_193
	ds_read_b128 v[220:223], v194
	ds_read_b128 v[224:227], v195
	s_and_b64 vcc, exec, s[20:21]
	s_waitcnt lgkmcnt(1)
	v_sub_f32_e32 v0, v219, v220
	v_mul_f32_e32 v0, 0x3fb8aa3b, v0
	v_exp_f32_e32 v149, v0
	v_sub_f32_e32 v1, v219, v221
	v_sub_f32_e32 v148, v219, v222
	v_mul_f32_e32 v1, 0x3fb8aa3b, v1
	v_mul_f32_e32 v0, 0x3fb8aa3b, v148
	v_exp_f32_e32 v148, v1
	s_waitcnt lgkmcnt(0)
	v_mul_f32_e32 v1, v224, v149
	v_mul_f32_e32 v1, v104, v1
	v_cndmask_b32_e64 v104, v1, 0, s[42:43]
	v_sub_f32_e32 v1, v219, v223
	v_mul_f32_e32 v1, 0x3fb8aa3b, v1
	v_exp_f32_e32 v0, v0
	v_exp_f32_e32 v1, v1
	v_mul_f32_e32 v148, v225, v148
	v_mul_f32_e32 v105, v105, v148
	v_cndmask_b32_e64 v105, 0, v105, s[44:45]
	v_pk_mul_f32 v[0:1], v[226:227], v[0:1]
	v_cvt_pk_bf16_f32 v104, v104, v105
	v_pk_mul_f32 v[0:1], v[106:107], v[0:1]
	s_nop 0
	v_cvt_pk_bf16_f32 v0, v0, v1
	v_cndmask_b32_e64 v1, v0, 0, s[48:49]
	v_lshrrev_b32_e32 v0, 16, v0
	v_cndmask_b32_e64 v0, v0, 0, s[46:47]
	v_perm_b32 v105, v0, v1, s3
	v_mov_b32_e32 v0, 0
	v_mov_b32_e32 v1, 0
	ds_write_b64 v3, v[104:105] offset:34816
	s_cbranch_vccnz .LBB0_174
	ds_read_b128 v[104:107], v194 offset:64
	ds_read_b128 v[220:223], v195 offset:64
	v_readlane_b32 s6, v254, 41
	v_readlane_b32 s7, v254, 42
	s_waitcnt lgkmcnt(1)
	v_sub_f32_e32 v0, v219, v104
	v_sub_f32_e32 v1, v219, v105
	v_mul_f32_e32 v0, 0x3fb8aa3b, v0
	v_mul_f32_e32 v1, 0x3fb8aa3b, v1
	v_exp_f32_e32 v0, v0
	v_exp_f32_e32 v1, v1
	v_sub_f32_e32 v104, v219, v106
	v_sub_f32_e32 v105, v219, v107
	v_mul_f32_e32 v104, 0x3fb8aa3b, v104
	v_mul_f32_e32 v105, 0x3fb8aa3b, v105
	v_exp_f32_e32 v104, v104
	v_exp_f32_e32 v105, v105
	s_waitcnt lgkmcnt(0)
	v_pk_mul_f32 v[0:1], v[220:221], v[0:1]
	s_nop 0
	v_pk_mul_f32 v[0:1], v[96:97], v[0:1]
	v_pk_mul_f32 v[96:97], v[222:223], v[104:105]
	v_cvt_pk_bf16_f32 v0, v0, v1
	v_cndmask_b32_e64 v1, v0, 0, s[4:5]
	v_lshrrev_b32_e32 v0, 16, v0
	v_pk_mul_f32 v[96:97], v[98:99], v[96:97]
	v_cndmask_b32_e64 v0, v0, 0, s[94:95]
	v_perm_b32 v0, v0, v1, s3
	v_cvt_pk_bf16_f32 v1, v96, v97
	v_cndmask_b32_e64 v96, v1, 0, s[6:7]
	v_readlane_b32 s6, v254, 39
	v_lshrrev_b32_e32 v1, 16, v1
	v_readlane_b32 s7, v254, 40
	s_nop 1
	v_cndmask_b32_e64 v1, v1, 0, s[6:7]
	v_perm_b32 v1, v1, v96, s3

; #define LAS __attribute__((address_space(3)))
; #define MFMA16(a, b, c) __builtin_amdgcn_mfma_f32_16x16x32_bf16((a), (b), (c), 0, 0, 0)
; #define MFMA16(a, b, c) __builtin_amdgcn_mfma_f32_16x16x32_bf16((a), (b), (c), 0, 0, 0)
; __device__ __forceinline__ void scan_prompt_unit(const Ctx& c, int b, int h) {
;     ...
;         for (int ks = 0; ks < 4; ++ks) {
;             if (ks <= (w >> 1)) {
;                 const bf16x8 wf = *(const LAS bf16x8*)(lds + SC_B + (16 * w + c16) * SROW + (32 * ks + 8 * q) * 2);
; #pragma unroll
;                 for (int pt = 0; pt < 4; ++pt) { const bf16x8 x_ = (ks < 2) ? xf[ks & 1][pt] : tr_frag(lds + SC_X, XROW, 32 * ks, 16 * pt, lane); yd[pt] = MFMA16(x_, wf, yd[pt]); }
;             }
;         }
.LBB0_189:
	s_andn2_b64 vcc, exec, s[76:77]
	s_cbranch_vccnz .LBB0_207
	ds_read_b128 v[92:95], v218 offset:34944
	ds_read_b64_tr_b16 v[98:99], v207 offset:9792
	ds_read_b64_tr_b16 v[96:97], v207 offset:9216
	ds_read_b64_tr_b16 v[100:101], v207 offset:9248
	ds_read_b64_tr_b16 v[102:103], v207 offset:9824
	s_waitcnt lgkmcnt(2)
	v_mfma_f32_16x16x32_bf16 v[88:91], v[96:99], v[92:95], v[88:91]
	ds_read_b64_tr_b16 v[96:97], v207 offset:9280
	ds_read_b64_tr_b16 v[98:99], v207 offset:9856
	s_waitcnt lgkmcnt(0)
	v_mfma_f32_16x16x32_bf16 v[80:83], v[96:99], v[92:95], v[80:83]
	ds_read_b64_tr_b16 v[96:97], v207 offset:9312
	ds_read_b64_tr_b16 v[98:99], v207 offset:9888
	v_mfma_f32_16x16x32_bf16 v[84:87], v[100:103], v[92:95], v[84:87]
	s_waitcnt lgkmcnt(0)
	v_mfma_f32_16x16x32_bf16 v[76:79], v[96:99], v[92:95], v[76:79]
	s_andn2_b64 vcc, exec, s[78:79]
	s_cbranch_vccnz .LBB0_147
	s_branch .LBB0_208
.LBB0_193:
	s_andn2_b64 vcc, exec, s[60:61]
	s_cbranch_vccnz .LBB0_175
